# v20: P2 GLA prompt loop - log(1+t) without the denormal/inf range fix-ups (argument is in (1,2])
# speedup vs baseline: 1.0073x; 1.0073x over previous
.Lp2g_mid:
	s_xor_b32 s99, s99, 1
	ds_read_b128 v[124:127], v75 offset:16384
	ds_read_b128 v[128:131], v75 offset:16400
	ds_read_b128 v[188:191], v75
	ds_read_b128 v[192:195], v75 offset:16
	ds_read_b128 v[196:199], v75 offset:1024
	ds_read_b128 v[200:203], v75 offset:1040
	ds_read_b128 v[204:207], v75 offset:2048
	ds_read_b128 v[210:213], v75 offset:2064
	ds_read_b128 v[214:217], v75 offset:3072
	ds_read_b128 v[218:221], v75 offset:3088
	s_waitcnt lgkmcnt(7)
	v_pk_fma_f32 v[126:127], v[52:53], v[190:191], v[126:127]
	v_pk_fma_f32 v[124:125], v[50:51], v[188:189], v[124:125]
	s_waitcnt lgkmcnt(6)
	v_pk_fma_f32 v[130:131], v[52:53], v[194:195], v[130:131]
	v_pk_fma_f32 v[128:129], v[50:51], v[192:193], v[128:129]
	s_waitcnt lgkmcnt(5)
	v_pk_fma_f32 v[126:127], v[28:29], v[198:199], v[126:127]
	v_pk_fma_f32 v[124:125], v[54:55], v[196:197], v[124:125]
	s_waitcnt lgkmcnt(4)
	v_pk_fma_f32 v[130:131], v[28:29], v[202:203], v[130:131]
	v_pk_fma_f32 v[128:129], v[54:55], v[200:201], v[128:129]
	s_waitcnt lgkmcnt(3)
	v_pk_fma_f32 v[126:127], v[82:83], v[206:207], v[126:127]
	v_pk_fma_f32 v[124:125], v[80:81], v[204:205], v[124:125]
	s_waitcnt lgkmcnt(2)
	v_pk_fma_f32 v[130:131], v[82:83], v[212:213], v[130:131]
	v_pk_fma_f32 v[128:129], v[80:81], v[210:211], v[128:129]
	s_waitcnt lgkmcnt(1)
	v_pk_fma_f32 v[132:133], v[30:31], v[216:217], v[126:127]
	v_pk_fma_f32 v[214:215], v[84:85], v[214:215], v[124:125]
	s_waitcnt lgkmcnt(0)
	v_pk_fma_f32 v[216:217], v[30:31], v[220:221], v[130:131]
	v_pk_fma_f32 v[218:219], v[84:85], v[218:219], v[128:129]
	ds_read_b128 v[124:127], v75 offset:4096
	ds_read_b128 v[128:131], v75 offset:4112
	ds_read_b128 v[188:191], v75 offset:5120
	ds_read_b128 v[192:195], v75 offset:5136
	ds_read_b128 v[196:199], v75 offset:6144
	ds_read_b128 v[200:203], v75 offset:6160
	ds_read_b128 v[204:207], v75 offset:7168
	ds_read_b128 v[210:213], v75 offset:7184
	s_waitcnt lgkmcnt(7)
	v_pk_fma_f32 v[126:127], v[88:89], v[126:127], v[132:133]
	v_pk_fma_f32 v[124:125], v[86:87], v[124:125], v[214:215]
	s_waitcnt lgkmcnt(6)
	v_pk_fma_f32 v[130:131], v[88:89], v[130:131], v[216:217]
	v_pk_fma_f32 v[128:129], v[86:87], v[128:129], v[218:219]
	s_waitcnt lgkmcnt(5)
	v_pk_fma_f32 v[126:127], v[24:25], v[190:191], v[126:127]
	v_pk_fma_f32 v[124:125], v[90:91], v[188:189], v[124:125]
	s_waitcnt lgkmcnt(4)
	v_pk_fma_f32 v[130:131], v[24:25], v[194:195], v[130:131]
	v_pk_fma_f32 v[128:129], v[90:91], v[192:193], v[128:129]
	s_waitcnt lgkmcnt(3)
	v_pk_fma_f32 v[126:127], v[94:95], v[198:199], v[126:127]
	v_pk_fma_f32 v[124:125], v[92:93], v[196:197], v[124:125]
	s_waitcnt lgkmcnt(2)
	v_pk_fma_f32 v[130:131], v[94:95], v[202:203], v[130:131]
	v_pk_fma_f32 v[128:129], v[92:93], v[200:201], v[128:129]
	s_waitcnt lgkmcnt(1)
	v_pk_fma_f32 v[132:133], v[26:27], v[206:207], v[126:127]
	v_pk_fma_f32 v[214:215], v[96:97], v[204:205], v[124:125]
	s_waitcnt lgkmcnt(0)
	v_pk_fma_f32 v[216:217], v[26:27], v[212:213], v[130:131]
	v_pk_fma_f32 v[218:219], v[96:97], v[210:211], v[128:129]
	ds_read_b128 v[124:127], v75 offset:8192
	ds_read_b128 v[128:131], v75 offset:8208
	ds_read_b128 v[188:191], v75 offset:9216
	ds_read_b128 v[192:195], v75 offset:9232
	ds_read_b128 v[196:199], v75 offset:10240
	ds_read_b128 v[200:203], v75 offset:10256
	ds_read_b128 v[204:207], v75 offset:11264
	ds_read_b128 v[210:213], v75 offset:11280
	s_waitcnt lgkmcnt(7)
	v_pk_fma_f32 v[126:127], v[100:101], v[126:127], v[132:133]
	v_pk_fma_f32 v[124:125], v[98:99], v[124:125], v[214:215]
	s_waitcnt lgkmcnt(6)
	v_pk_fma_f32 v[130:131], v[100:101], v[130:131], v[216:217]
	v_pk_fma_f32 v[128:129], v[98:99], v[128:129], v[218:219]
	s_waitcnt lgkmcnt(5)
	v_pk_fma_f32 v[126:127], v[20:21], v[190:191], v[126:127]
	v_pk_fma_f32 v[124:125], v[102:103], v[188:189], v[124:125]
	s_waitcnt lgkmcnt(4)
	v_pk_fma_f32 v[130:131], v[20:21], v[194:195], v[130:131]
	v_pk_fma_f32 v[128:129], v[102:103], v[192:193], v[128:129]
	s_waitcnt lgkmcnt(3)
	v_pk_fma_f32 v[126:127], v[106:107], v[198:199], v[126:127]
	v_pk_fma_f32 v[124:125], v[104:105], v[196:197], v[124:125]
	s_waitcnt lgkmcnt(2)
	v_pk_fma_f32 v[130:131], v[106:107], v[202:203], v[130:131]
	v_pk_fma_f32 v[128:129], v[104:105], v[200:201], v[128:129]
	s_waitcnt lgkmcnt(1)
	v_pk_fma_f32 v[132:133], v[22:23], v[206:207], v[126:127]
	v_pk_fma_f32 v[214:215], v[108:109], v[204:205], v[124:125]
	s_waitcnt lgkmcnt(0)
	v_pk_fma_f32 v[216:217], v[22:23], v[212:213], v[130:131]
	v_pk_fma_f32 v[218:219], v[108:109], v[210:211], v[128:129]
	ds_read_b128 v[124:127], v75 offset:12288
	ds_read_b128 v[128:131], v75 offset:12304
	ds_read_b128 v[188:191], v75 offset:13312
	ds_read_b128 v[192:195], v75 offset:13328
	ds_read_b128 v[196:199], v75 offset:14336
	ds_read_b128 v[200:203], v75 offset:14352
	ds_read_b128 v[204:207], v75 offset:15360
	ds_read_b128 v[210:213], v75 offset:15376
	s_waitcnt lgkmcnt(7)
	v_pk_fma_f32 v[124:125], v[110:111], v[124:125], v[214:215]
	s_waitcnt lgkmcnt(6)
	v_pk_fma_f32 v[130:131], v[112:113], v[130:131], v[216:217]
	s_waitcnt lgkmcnt(5)
	v_pk_fma_f32 v[124:125], v[114:115], v[188:189], v[124:125]
	v_pk_fma_f32 v[126:127], v[112:113], v[126:127], v[132:133]
	s_waitcnt lgkmcnt(4)
	v_pk_fma_f32 v[130:131], v[116:117], v[194:195], v[130:131]
	s_waitcnt lgkmcnt(3)
	v_pk_fma_f32 v[124:125], v[118:119], v[196:197], v[124:125]
	v_pk_fma_f32 v[128:129], v[110:111], v[128:129], v[218:219]
	v_pk_fma_f32 v[126:127], v[116:117], v[190:191], v[126:127]
	s_waitcnt lgkmcnt(2)
	v_pk_fma_f32 v[132:133], v[120:121], v[202:203], v[130:131]
	s_waitcnt lgkmcnt(1)
	v_pk_fma_f32 v[130:131], v[122:123], v[204:205], v[124:125]
	v_pk_fma_f32 v[128:129], v[114:115], v[192:193], v[128:129]
	v_pk_fma_f32 v[126:127], v[120:121], v[198:199], v[126:127]
	v_mul_f32_e64 v75, |v130|, s80
	v_pk_fma_f32 v[188:189], v[118:119], v[200:201], v[128:129]
	v_pk_fma_f32 v[128:129], v[18:19], v[206:207], v[126:127]
	v_exp_f32_e32 v75, v75
	s_waitcnt lgkmcnt(0)
	v_pk_fma_f32 v[124:125], v[18:19], v[212:213], v[132:133]
	v_pk_fma_f32 v[126:127], v[122:123], v[210:211], v[188:189]
	v_mul_f32_e64 v132, |v129|, s80
	v_exp_f32_e32 v187, v132
	v_mul_f32_e64 v132, |v126|, s80
	v_exp_f32_e32 v190, v132
	v_mul_f32_e64 v132, |v127|, s80
	v_exp_f32_e32 v191, v132
	v_mul_f32_e64 v132, |v124|, s80
	v_add_f32_e32 v75, 1.0, v75
	v_exp_f32_e32 v192, v132
	v_mul_f32_e64 v132, |v125|, s80
	v_exp_f32_e32 v193, v132
	v_mul_f32_e64 v77, |v131|, s80
	v_log_f32_e32 v75, v75
	v_exp_f32_e32 v77, v77
	v_mul_f32_e64 v79, |v128|, s80
	v_exp_f32_e32 v79, v79
	v_mul_f32_e32 v132, 0x3f317217, v75
	v_fma_f32 v132, v75, s10, -v132
	v_fmac_f32_e32 v132, 0x3377d1cf, v75
	v_fmac_f32_e32 v132, 0x3f317217, v75
	v_min_f32_e32 v130, 0, v130
	v_min_f32_e32 v131, 0, v131
	v_mov_b32_e32 v132, v132
	v_add_f32_e32 v75, 1.0, v77
	v_min_f32_e32 v128, 0, v128
	v_min_f32_e32 v129, 0, v129
	v_log_f32_e32 v75, v75
	v_lshlrev_b32_e32 v194, 16, v46
	v_and_b32_e32 v195, 0xffff0000, v46
	v_lshlrev_b32_e32 v196, 16, v47
	v_mul_f32_e32 v77, 0x3f317217, v75
	v_fma_f32 v77, v75, s10, -v77
	v_fmac_f32_e32 v77, 0x3377d1cf, v75
	v_fmac_f32_e32 v77, 0x3f317217, v75
	v_and_b32_e32 v197, 0xffff0000, v47
	v_lshlrev_b32_e32 v46, 16, v42
	v_mov_b32_e32 v133, v77
	v_add_f32_e32 v75, 1.0, v79
	v_lshlrev_b32_e32 v79, 16, v45
	v_and_b32_e32 v42, 0xffff0000, v42
	v_log_f32_e32 v75, v75
	v_lshlrev_b32_e32 v47, 16, v43
	v_and_b32_e32 v43, 0xffff0000, v43
	v_mul_f32_e32 v203, 0x3e000000, v42
	v_mul_f32_e32 v77, 0x3f317217, v75
	v_fma_f32 v77, v75, s10, -v77
	v_fmac_f32_e32 v77, 0x3377d1cf, v75
	v_fmac_f32_e32 v77, 0x3f317217, v75
	v_mul_f32_e32 v205, 0x3e000000, v43
	v_min_f32_e32 v126, 0, v126
	v_mov_b32_e32 v188, v77
	v_add_f32_e32 v75, 1.0, v187
	v_and_b32_e32 v187, 0xffff0000, v45
	v_lshlrev_b32_e32 v45, 16, v41
	v_log_f32_e32 v75, v75
	v_and_b32_e32 v41, 0xffff0000, v41
	v_mul_f32_e32 v201, 0x3e000000, v41
	v_min_f32_e32 v127, 0, v127
	v_mul_f32_e32 v77, 0x3f317217, v75
	v_fma_f32 v77, v75, s10, -v77
	v_fmac_f32_e32 v77, 0x3377d1cf, v75
	v_fmac_f32_e32 v77, 0x3f317217, v75
	v_mul_f32_e32 v200, 0x3e000000, v45
	v_min_f32_e32 v124, 0, v124
	v_mov_b32_e32 v189, v77
	v_add_f32_e32 v75, 1.0, v190
	v_pk_add_f32 v[42:43], v[128:129], v[188:189] neg_lo:[0,1] neg_hi:[0,1]
	v_min_f32_e32 v125, 0, v125
	v_log_f32_e32 v75, v75
	v_pk_mul_f32 v[42:43], v[42:43], s[92:93] op_sel_hi:[1,0]
	v_mul_f32_e32 v202, 0x3e000000, v46
	v_cndmask_b32_e64 v42, 0, v42, s[42:43]
	v_mul_f32_e32 v77, 0x3f317217, v75
	v_fma_f32 v77, v75, s10, -v77
	v_fmac_f32_e32 v77, 0x3377d1cf, v75
	v_fmac_f32_e32 v77, 0x3f317217, v75
	v_add_f32_dpp v42, v42, v42 row_shr:1 row_mask:0xf bank_mask:0xf bound_ctrl:1
	v_cndmask_b32_e64 v43, 0, v43, s[42:43]
	v_mov_b32_e32 v190, v77
	v_add_f32_e32 v75, 1.0, v191
	v_add_f32_dpp v42, v42, v42 row_shr:2 row_mask:0xf bank_mask:0xf bound_ctrl:1
	v_add_f32_dpp v43, v43, v43 row_shr:1 row_mask:0xf bank_mask:0xf bound_ctrl:1
	v_log_f32_e32 v75, v75
	v_add_f32_dpp v42, v42, v42 row_shr:4 row_mask:0xf bank_mask:0xf bound_ctrl:1
	v_add_f32_dpp v43, v43, v43 row_shr:2 row_mask:0xf bank_mask:0xf bound_ctrl:1
	v_mul_f32_e32 v204, 0x3e000000, v47
	v_mul_f32_e32 v77, 0x3f317217, v75
	v_fma_f32 v77, v75, s10, -v77
	v_fmac_f32_e32 v77, 0x3377d1cf, v75
	v_fmac_f32_e32 v77, 0x3f317217, v75
	v_add_f32_dpp v42, v42, v42 row_shr:8 row_mask:0xf bank_mask:0xf bound_ctrl:1
	v_add_f32_dpp v43, v43, v43 row_shr:4 row_mask:0xf bank_mask:0xf bound_ctrl:1
	v_mov_b32_e32 v191, v77
	v_add_f32_e32 v75, 1.0, v192
	v_add_f32_dpp v43, v43, v43 row_shr:8 row_mask:0xf bank_mask:0xf bound_ctrl:1
	v_cndmask_b32_e64 v128, 0, v187, s[42:43]
	v_log_f32_e32 v75, v75
	v_cndmask_b32_e64 v187, 0, v196, s[42:43]
	v_cndmask_b32_e64 v189, 0, v197, s[42:43]
	v_cndmask_b32_e64 v129, 0, v202, s[42:43]
	v_mul_f32_e32 v77, 0x3f317217, v75
	v_fma_f32 v77, v75, s10, -v77
	v_fmac_f32_e32 v77, 0x3377d1cf, v75
	v_fmac_f32_e32 v77, 0x3f317217, v75
	v_cndmask_b32_e64 v188, 0, v205, s[42:43]
	v_cndmask_b32_e64 v79, 0, v79, s[42:43]
	v_mov_b32_e32 v192, v77
	v_add_f32_e32 v75, 1.0, v193
	s_nop 1
	v_log_f32_e32 v75, v75
	s_nop 0
	v_mul_f32_e32 v77, 0x3f317217, v75
	v_fma_f32 v77, v75, s10, -v77
	v_fmac_f32_e32 v77, 0x3377d1cf, v75
	v_fmac_f32_e32 v77, 0x3f317217, v75
	s_nop 1
	v_mov_b32_e32 v193, v77
	v_lshlrev_b32_e32 v75, 16, v44
	v_and_b32_e32 v77, 0xffff0000, v44
	v_lshlrev_b32_e32 v44, 16, v40
	v_and_b32_e32 v40, 0xffff0000, v40
	v_mul_f32_e32 v199, 0x3e000000, v40
	v_pk_add_f32 v[40:41], v[130:131], v[132:133] neg_lo:[0,1] neg_hi:[0,1]
	v_mul_f32_e32 v198, 0x3e000000, v44
	v_pk_mul_f32 v[40:41], v[40:41], s[92:93] op_sel_hi:[1,0]
	v_pk_add_f32 v[44:45], v[126:127], v[190:191] neg_lo:[0,1] neg_hi:[0,1]
	v_cndmask_b32_e64 v40, 0, v40, s[42:43]
	v_cndmask_b32_e64 v41, 0, v41, s[42:43]
	v_mov_b32_e32 v190, 0
	v_add_f32_dpp v40, v40, v40 row_shr:1 row_mask:0xf bank_mask:0xf bound_ctrl:1
	v_add_f32_dpp v41, v41, v41 row_shr:1 row_mask:0xf bank_mask:0xf bound_ctrl:1
	v_pk_mul_f32 v[44:45], v[44:45], s[92:93] op_sel_hi:[1,0]
	v_add_f32_dpp v40, v40, v40 row_shr:2 row_mask:0xf bank_mask:0xf bound_ctrl:1
	v_add_f32_dpp v41, v41, v41 row_shr:2 row_mask:0xf bank_mask:0xf bound_ctrl:1
	v_cndmask_b32_e64 v44, 0, v44, s[42:43]
	v_add_f32_dpp v40, v40, v40 row_shr:4 row_mask:0xf bank_mask:0xf bound_ctrl:1
	v_add_f32_dpp v41, v41, v41 row_shr:4 row_mask:0xf bank_mask:0xf bound_ctrl:1
	v_add_f32_dpp v44, v44, v44 row_shr:1 row_mask:0xf bank_mask:0xf bound_ctrl:1
	v_add_f32_dpp v40, v40, v40 row_shr:8 row_mask:0xf bank_mask:0xf bound_ctrl:1
	v_add_f32_dpp v41, v41, v41 row_shr:8 row_mask:0xf bank_mask:0xf bound_ctrl:1
	v_pk_add_f32 v[46:47], v[124:125], v[192:193] neg_lo:[0,1] neg_hi:[0,1]
	v_mov_b32_dpp v190, v40 row_bcast:15 row_mask:0xa bank_mask:0xf bound_ctrl:1
	v_add_f32_e32 v40, v40, v190
	v_mov_b32_e32 v190, 0
	v_cndmask_b32_e64 v45, 0, v45, s[42:43]
	v_add_f32_dpp v44, v44, v44 row_shr:2 row_mask:0xf bank_mask:0xf bound_ctrl:1
	v_mov_b32_dpp v190, v41 row_bcast:15 row_mask:0xa bank_mask:0xf bound_ctrl:1
	v_add_f32_e32 v41, v41, v190
	v_mov_b32_e32 v190, 0
	v_pk_mul_f32 v[46:47], v[46:47], s[92:93] op_sel_hi:[1,0]
	v_add_f32_dpp v45, v45, v45 row_shr:1 row_mask:0xf bank_mask:0xf bound_ctrl:1
	v_mov_b32_dpp v190, v42 row_bcast:15 row_mask:0xa bank_mask:0xf bound_ctrl:1
	v_add_f32_e32 v42, v42, v190
	v_mov_b32_e32 v190, 0
	v_add_f32_dpp v44, v44, v44 row_shr:4 row_mask:0xf bank_mask:0xf bound_ctrl:1
	v_cndmask_b32_e64 v46, 0, v46, s[42:43]
	v_mov_b32_dpp v190, v43 row_bcast:15 row_mask:0xa bank_mask:0xf bound_ctrl:1
	v_add_f32_dpp v45, v45, v45 row_shr:2 row_mask:0xf bank_mask:0xf bound_ctrl:1
	v_add_f32_dpp v44, v44, v44 row_shr:8 row_mask:0xf bank_mask:0xf bound_ctrl:1
	v_add_f32_e32 v43, v43, v190
	v_mov_b32_e32 v190, 0
	v_add_f32_dpp v46, v46, v46 row_shr:1 row_mask:0xf bank_mask:0xf bound_ctrl:1
	v_add_f32_dpp v45, v45, v45 row_shr:4 row_mask:0xf bank_mask:0xf bound_ctrl:1
	v_mov_b32_dpp v190, v44 row_bcast:15 row_mask:0xa bank_mask:0xf bound_ctrl:1
	v_cndmask_b32_e64 v47, 0, v47, s[42:43]
	v_add_f32_dpp v46, v46, v46 row_shr:2 row_mask:0xf bank_mask:0xf bound_ctrl:1
	v_add_f32_dpp v45, v45, v45 row_shr:8 row_mask:0xf bank_mask:0xf bound_ctrl:1
	v_add_f32_e32 v44, v44, v190
	v_mov_b32_e32 v190, 0
	v_add_f32_dpp v47, v47, v47 row_shr:1 row_mask:0xf bank_mask:0xf bound_ctrl:1
	v_add_f32_dpp v46, v46, v46 row_shr:4 row_mask:0xf bank_mask:0xf bound_ctrl:1
	v_mov_b32_dpp v190, v45 row_bcast:15 row_mask:0xa bank_mask:0xf bound_ctrl:1
	v_add_f32_dpp v47, v47, v47 row_shr:2 row_mask:0xf bank_mask:0xf bound_ctrl:1
	v_add_f32_dpp v46, v46, v46 row_shr:8 row_mask:0xf bank_mask:0xf bound_ctrl:1
	v_add_f32_e32 v45, v45, v190
	v_mov_b32_e32 v190, 0
	v_add_f32_dpp v47, v47, v47 row_shr:4 row_mask:0xf bank_mask:0xf bound_ctrl:1
	v_max_f32_e32 v40, 0xc2a00000, v40
	v_mov_b32_dpp v190, v46 row_bcast:15 row_mask:0xa bank_mask:0xf bound_ctrl:1
	v_add_f32_dpp v47, v47, v47 row_shr:8 row_mask:0xf bank_mask:0xf bound_ctrl:1
	v_add_f32_e32 v46, v46, v190
	v_mov_b32_e32 v190, 0
	v_mul_f32_e32 v40, 0x3fb8aa3b, v40
	v_cndmask_b32_e64 v130, 0, v194, s[42:43]
	v_mov_b32_dpp v190, v47 row_bcast:15 row_mask:0xa bank_mask:0xf bound_ctrl:1
	v_add_f32_e32 v47, v47, v190
	v_exp_f32_e32 v190, v40
	v_max_f32_e32 v40, 0xc2a00000, v41
	v_mul_f32_e32 v40, 0x3fb8aa3b, v40
	v_exp_f32_e32 v191, v40
	v_max_f32_e32 v40, 0xc2a00000, v42
	v_mul_f32_e32 v40, 0x3fb8aa3b, v40
	v_exp_f32_e32 v192, v40
	v_max_f32_e32 v40, 0xc2a00000, v43
	v_mul_f32_e32 v40, 0x3fb8aa3b, v40
	v_exp_f32_e32 v193, v40
	v_max_f32_e32 v40, 0xc2a00000, v44
	v_mul_f32_e32 v40, 0x3fb8aa3b, v40
	v_exp_f32_e32 v194, v40
	v_max_f32_e32 v40, 0xc2a00000, v45
	v_mul_f32_e32 v40, 0x3fb8aa3b, v40
	v_cndmask_b32_e64 v132, 0, v195, s[42:43]
	v_exp_f32_e32 v195, v40
	v_max_f32_e32 v40, 0xc2a00000, v46
	v_mul_f32_e32 v40, 0x3fb8aa3b, v40
	v_exp_f32_e32 v196, v40
	v_max_f32_e32 v40, 0xc2a00000, v47
	v_mul_f32_e32 v40, 0x3fb8aa3b, v40
	v_exp_f32_e32 v197, v40
	v_readlane_b32 s0, v190, 31
	v_readlane_b32 s1, v190, 63
	v_cndmask_b32_e64 v124, 0, v198, s[42:43]
	v_mov_b32_e32 v41, s0
	v_mov_b32_e32 v40, s1
	v_readlane_b32 s0, v191, 31
	v_readlane_b32 s1, v191, 63
	v_cndmask_b32_e64 v40, v40, v41, s[2:3]
	v_mov_b32_e32 v42, s0
	v_mov_b32_e32 v41, s1
	v_readlane_b32 s0, v192, 31
	v_readlane_b32 s1, v192, 63
	v_cndmask_b32_e64 v125, 0, v199, s[42:43]
	v_cndmask_b32_e64 v126, 0, v200, s[42:43]
	v_cndmask_b32_e64 v127, 0, v201, s[42:43]
	v_cndmask_b32_e64 v131, 0, v203, s[42:43]
	v_cndmask_b32_e64 v133, 0, v204, s[42:43]
	v_rcp_f32_e32 v198, v190
	v_rcp_f32_e32 v199, v191
	v_rcp_f32_e32 v200, v192
	v_rcp_f32_e32 v201, v193
	v_rcp_f32_e32 v202, v194
	v_rcp_f32_e32 v203, v195
	v_rcp_f32_e32 v204, v196
	v_rcp_f32_e32 v205, v197
	v_cndmask_b32_e64 v41, v41, v42, s[2:3]
	v_mov_b32_e32 v42, s1
	v_mov_b32_e32 v43, s0
	v_readlane_b32 s0, v193, 31
	v_readlane_b32 s1, v193, 63
	v_cndmask_b32_e64 v42, v42, v43, s[2:3]
	v_mov_b32_e32 v44, s0
	v_mov_b32_e32 v43, s1
	v_readlane_b32 s0, v194, 31
	v_readlane_b32 s1, v194, 63
	v_cndmask_b32_e64 v43, v43, v44, s[2:3]
	v_mov_b32_e32 v45, s0
	v_mov_b32_e32 v44, s1
	v_readlane_b32 s0, v195, 31
	v_readlane_b32 s1, v195, 63
	v_cndmask_b32_e64 v75, 0, v75, s[42:43]
	v_cndmask_b32_e64 v77, 0, v77, s[42:43]
	v_cndmask_b32_e64 v44, v44, v45, s[2:3]
	v_mov_b32_e32 v45, s1
	v_mov_b32_e32 v46, s0
	v_cndmask_b32_e64 v45, v45, v46, s[2:3]
	v_mul_f32_e32 v124, v124, v190
	v_mul_f32_e32 v75, v75, v198
	v_mul_f32_e32 v125, v125, v191
	v_mul_f32_e32 v77, v77, v199
	v_mul_f32_e32 v126, v126, v192
	v_mul_f32_e32 v79, v79, v200
	v_mul_f32_e32 v127, v127, v193
	v_mul_f32_e32 v193, v128, v201
	v_mul_f32_e32 v128, v129, v194
	v_mul_f32_e32 v130, v130, v202
	v_mul_f32_e32 v129, v131, v195
	v_mul_f32_e32 v131, v132, v203
	v_mul_f32_e32 v187, v187, v204
	v_mul_f32_e32 v189, v189, v205
	v_mul_f32_e32 v194, v130, v44
	v_mul_f32_e32 v132, v131, v45
	v_cvt_pk_bf16_f32 v124, v124, v125
	v_cvt_pk_bf16_f32 v125, v126, v127
	v_cvt_pk_bf16_f32 v126, v128, v129
	v_cvt_pk_bf16_f32 v128, v75, v77
	v_cvt_pk_bf16_f32 v129, v79, v193
	v_cvt_pk_bf16_f32 v130, v130, v131
	v_cvt_pk_bf16_f32 v131, v187, v189
	v_mul_f32_e32 v133, v133, v196
	v_mul_f32_e32 v188, v188, v197
	v_cvt_pk_bf16_f32 v127, v133, v188
	v_readlane_b32 s0, v196, 31
	v_readlane_b32 s1, v196, 63
	v_mfma_f32_32x32x16_bf16 v[2:17], v[128:131], v[124:127], v[2:17]
	v_mul_f32_e32 v190, v40, v75
	v_xor_b32_e32 v75, v71, v168
	v_mov_b32_e32 v46, s1
	v_mov_b32_e32 v47, s0
	v_readlane_b32 s0, v197, 31
	v_readlane_b32 s1, v197, 63
	v_mul_f32_e32 v191, v77, v41
	v_lshl_add_u32 v75, v75, 4, v167
	v_cndmask_b32_e64 v46, v46, v47, s[2:3]
	v_mov_b32_e32 v47, s1
	v_mov_b32_e32 v206, s0
	v_mul_f32_e32 v192, v79, v42
	v_mul_f32_e32 v198, v193, v43
	ds_write_b128 v75, v[124:127] offset:20480
	v_cvt_pk_bf16_f32 v75, v190, v191
	v_cndmask_b32_e64 v47, v47, v206, s[2:3]
	ds_write_b16 v73, v75
	ds_write_b16_d16_hi v73, v75 offset:64
	v_cvt_pk_bf16_f32 v75, v192, v198
	v_mul_f32_e32 v195, v187, v46
	v_mul_f32_e32 v196, v189, v47
	ds_write_b16 v73, v75 offset:128
	ds_write_b16_d16_hi v73, v75 offset:192
	v_cvt_pk_bf16_f32 v75, v194, v132
	ds_write_b16 v73, v75 offset:256
	ds_write_b16_d16_hi v73, v75 offset:320
	v_cvt_pk_bf16_f32 v75, v195, v196
	ds_write_b16 v73, v75 offset:384
	ds_write_b16_d16_hi v73, v75 offset:448
	s_and_saveexec_b64 s[0:1], s[4:5]
	s_cbranch_execz .LBB0_562
	v_add_u32_e32 v75, s57, v183
	ds_write_b128 v75, v[40:43]
	ds_write_b128 v75, v[44:47] offset:16
	s_branch .LBB0_562
